# selected-branch QK^T: all eight K-fragment LDS reads of a key block issued up front (second batch into a free quad), counted waits
# baseline (speedup 1.0000x reference)
.LBB0_753:
	s_lshl_b32 s5, s70, 15
	s_add_i32 s75, s5, 0
	v_lshl_add_u32 v3, v163, 1, s75
	v_lshl_add_u32 v0, v164, 1, v3
	ds_read_b128 v[112:115], v0
	ds_read_b128 v[128:131], v0 offset:2048
	s_lshl_b32 s5, 1, s4
	v_and_b32_e32 v2, s5, v152
	v_cmp_ne_u32_e32 vcc, 0, v2
	v_lshl_add_u32 v2, v165, 1, v3
	ds_read_b128 v[116:119], v2
	ds_read_b128 v[136:139], v2 offset:2048
	ds_read_b128 v[198:201], v0 offset:4096
	ds_read_b128 v[182:185], v0 offset:6144
	ds_read_b128 v[186:189], v2 offset:4096
	ds_read_b128 v[190:193], v2 offset:6144
	v_and_b32_e32 v132, s5, v153
	v_cndmask_b32_e64 v124, v158, -v154, vcc
	v_cmp_ne_u32_e32 vcc, 0, v132
	v_mov_b32_e32 v125, v124
	v_mov_b32_e32 v126, v124
	v_cndmask_b32_e64 v178, v158, -v154, vcc
	v_mov_b32_e32 v127, v124
	v_mov_b32_e32 v179, v178
	v_mov_b32_e32 v180, v178
	v_mov_b32_e32 v181, v178
	s_waitcnt lgkmcnt(7)
	v_mfma_f32_16x16x32_bf16 v[120:123], v[112:115], v[4:7], v[124:127]
	s_cmp_lg_u32 s4, s63
	v_mfma_f32_16x16x32_bf16 v[112:115], v[112:115], v[12:15], v[178:181]
	s_waitcnt lgkmcnt(5)
	v_mfma_f32_16x16x32_bf16 v[132:135], v[116:119], v[16:19], v[112:115]
	v_mfma_f32_16x16x32_bf16 v[112:115], v[128:131], v[4:7], v[124:127]
	v_mfma_f32_16x16x32_bf16 v[120:123], v[116:119], v[8:11], v[120:123]
	s_waitcnt lgkmcnt(4)
	v_mfma_f32_16x16x32_bf16 v[116:119], v[136:139], v[8:11], v[112:115]
	v_mfma_f32_16x16x32_bf16 v[112:115], v[128:131], v[12:15], v[178:181]
	v_mfma_f32_16x16x32_bf16 v[112:115], v[136:139], v[16:19], v[112:115]
	s_waitcnt lgkmcnt(3)
	v_mfma_f32_16x16x32_bf16 v[136:139], v[198:201], v[4:7], v[124:127]
	v_mfma_f32_16x16x32_bf16 v[128:131], v[198:201], v[12:15], v[178:181]
	s_waitcnt lgkmcnt(1)
	v_mfma_f32_16x16x32_bf16 v[140:143], v[186:189], v[8:11], v[136:139]
	v_mfma_f32_16x16x32_bf16 v[136:139], v[186:189], v[16:19], v[128:131]
	v_mfma_f32_16x16x32_bf16 v[124:127], v[182:185], v[4:7], v[124:127]
	v_mfma_f32_16x16x32_bf16 v[128:131], v[182:185], v[12:15], v[178:181]
	s_waitcnt lgkmcnt(0)
	v_mfma_f32_16x16x32_bf16 v[124:127], v[190:193], v[8:11], v[124:127]
	v_mfma_f32_16x16x32_bf16 v[128:131], v[190:193], v[16:19], v[128:131]
	s_cbranch_scc1 .LBB0_755
	v_mov_b32_e32 v3, v176
	v_mov_b32_e32 v155, v166
	s_nop 0
	v_sub_u32_e32 v3, v3, v155
	v_cmp_lt_i32_e64 s[10:11], s43, v3
	v_cmp_gt_i32_e32 vcc, 0, v3
	v_cmp_gt_i32_e64 s[4:5], 1, v3
	v_cndmask_b32_e64 v132, v158, v132, s[10:11]
	v_cmp_lt_i32_e64 s[10:11], -16, v3
	v_cmp_gt_i32_e64 s[6:7], 2, v3
	v_cmp_gt_i32_e64 s[8:9], 3, v3
	v_cndmask_b32_e64 v133, v158, v133, s[10:11]
	v_cmp_lt_i32_e64 s[10:11], -15, v3
	v_cndmask_b32_e32 v120, v120, v158, vcc
	v_cndmask_b32_e64 v121, v121, v158, s[4:5]
	v_cndmask_b32_e64 v134, v158, v134, s[10:11]
	v_cmp_lt_i32_e64 s[10:11], -14, v3
	v_cndmask_b32_e64 v122, v122, v158, s[6:7]
	v_cndmask_b32_e64 v123, v123, v158, s[8:9]
	v_cndmask_b32_e64 v135, v158, v135, s[10:11]
	v_cmp_gt_i32_e64 s[10:11], 16, v3
	v_cmp_gt_i32_e64 s[12:13], 17, v3
	v_cmp_gt_i32_e64 s[14:15], 18, v3
	v_cndmask_b32_e64 v116, v116, v158, s[10:11]
	v_cndmask_b32_e64 v136, v136, v158, s[10:11]
	v_cmp_lt_i32_e64 s[10:11], 47, v3
	v_cmp_gt_i32_e64 s[16:17], 19, v3
	v_cndmask_b32_e32 v112, v112, v158, vcc
	v_cndmask_b32_e64 v124, v158, v124, s[10:11]
	v_cmp_lt_i32_e64 s[10:11], 48, v3
	v_cndmask_b32_e64 v113, v113, v158, s[4:5]
	v_cndmask_b32_e64 v114, v114, v158, s[6:7]
	v_cndmask_b32_e64 v125, v158, v125, s[10:11]
	v_cmp_lt_i32_e64 s[10:11], 49, v3
	v_cndmask_b32_e64 v115, v115, v158, s[8:9]
	v_cmp_gt_i32_e32 vcc, 32, v3
	v_cmp_gt_i32_e64 s[4:5], 33, v3
	v_cmp_gt_i32_e64 s[6:7], 34, v3
	v_cmp_gt_i32_e64 s[8:9], 35, v3
	v_cndmask_b32_e64 v126, v158, v126, s[10:11]
	v_cmp_lt_i32_e64 s[10:11], 50, v3
	v_cndmask_b32_e64 v117, v117, v158, s[12:13]
	v_cndmask_b32_e64 v118, v118, v158, s[14:15]
	v_cndmask_b32_e64 v119, v119, v158, s[16:17]
	v_cndmask_b32_e32 v140, v140, v158, vcc
	v_cndmask_b32_e64 v141, v141, v158, s[4:5]
	v_cndmask_b32_e64 v142, v142, v158, s[6:7]
	v_cndmask_b32_e64 v143, v143, v158, s[8:9]
	v_cndmask_b32_e64 v137, v137, v158, s[12:13]
	v_cndmask_b32_e64 v138, v138, v158, s[14:15]
	v_cndmask_b32_e64 v139, v139, v158, s[16:17]
	v_cndmask_b32_e64 v127, v158, v127, s[10:11]
	v_cndmask_b32_e32 v128, v128, v158, vcc
	v_cndmask_b32_e64 v129, v129, v158, s[4:5]
	v_cndmask_b32_e64 v130, v130, v158, s[6:7]
	v_cndmask_b32_e64 v131, v131, v158, s[8:9]
.LBB0_755:
	s_cmp_gt_i32 s76, -1
	s_cselect_b64 s[34:35], -1, 0
	s_cmp_lt_i32 s76, 0
	s_cbranch_scc1 .LBB0_758
	ds_read_b128 v[80:83], v0 offset:16384
	ds_read_b128 v[96:99], v0 offset:18432
	s_lshl_b32 s4, 1, s76
	v_and_b32_e32 v3, s4, v152
	ds_read_b128 v[84:87], v2 offset:16384
	ds_read_b128 v[104:107], v2 offset:18432
	ds_read_b128 v[194:197], v0 offset:20480
	ds_read_b128 v[182:185], v0 offset:22528
	ds_read_b128 v[186:189], v2 offset:20480
	ds_read_b128 v[190:193], v2 offset:22528
	v_cmp_ne_u32_e32 vcc, 0, v3
	v_and_b32_e32 v3, s4, v153
	s_cmp_lg_u32 s76, s63
	v_cndmask_b32_e64 v92, v158, -v154, vcc
	v_cmp_ne_u32_e32 vcc, 0, v3
	v_mov_b32_e32 v93, v92
	v_mov_b32_e32 v94, v92
	v_cndmask_b32_e64 v178, v158, -v154, vcc
	v_mov_b32_e32 v95, v92
	v_mov_b32_e32 v179, v178
	v_mov_b32_e32 v180, v178
	v_mov_b32_e32 v181, v178
	s_waitcnt lgkmcnt(7)
	v_mfma_f32_16x16x32_bf16 v[88:91], v[80:83], v[4:7], v[92:95]
	v_mfma_f32_16x16x32_bf16 v[80:83], v[80:83], v[12:15], v[178:181]
	s_waitcnt lgkmcnt(5)
	v_mfma_f32_16x16x32_bf16 v[100:103], v[84:87], v[16:19], v[80:83]
	v_mfma_f32_16x16x32_bf16 v[80:83], v[96:99], v[4:7], v[92:95]
	v_mfma_f32_16x16x32_bf16 v[88:91], v[84:87], v[8:11], v[88:91]
	s_waitcnt lgkmcnt(4)
	v_mfma_f32_16x16x32_bf16 v[84:87], v[104:107], v[8:11], v[80:83]
	v_mfma_f32_16x16x32_bf16 v[80:83], v[96:99], v[12:15], v[178:181]
	v_mfma_f32_16x16x32_bf16 v[80:83], v[104:107], v[16:19], v[80:83]
	s_waitcnt lgkmcnt(3)
	v_mfma_f32_16x16x32_bf16 v[104:107], v[194:197], v[4:7], v[92:95]
	v_mfma_f32_16x16x32_bf16 v[96:99], v[194:197], v[12:15], v[178:181]
	s_waitcnt lgkmcnt(1)
	v_mfma_f32_16x16x32_bf16 v[108:111], v[186:189], v[8:11], v[104:107]
	v_mfma_f32_16x16x32_bf16 v[104:107], v[186:189], v[16:19], v[96:99]
	v_mfma_f32_16x16x32_bf16 v[92:95], v[182:185], v[4:7], v[92:95]
	v_mfma_f32_16x16x32_bf16 v[96:99], v[182:185], v[12:15], v[178:181]
	s_waitcnt lgkmcnt(0)
	v_mfma_f32_16x16x32_bf16 v[92:95], v[190:193], v[8:11], v[92:95]
	v_mfma_f32_16x16x32_bf16 v[96:99], v[190:193], v[16:19], v[96:99]
	s_cbranch_scc1 .LBB0_758
	v_mov_b32_e32 v0, v176
	v_mov_b32_e32 v2, v166
	s_nop 0
	v_sub_u32_e32 v0, v0, v2
	v_cmp_lt_i32_e64 s[10:11], s43, v0
	v_cmp_gt_i32_e32 vcc, 0, v0
	v_cmp_gt_i32_e64 s[4:5], 1, v0
	v_cndmask_b32_e64 v100, v158, v100, s[10:11]
	v_cmp_lt_i32_e64 s[10:11], -16, v0
	v_cmp_gt_i32_e64 s[6:7], 2, v0
	v_cmp_gt_i32_e64 s[8:9], 3, v0
	v_cndmask_b32_e64 v101, v158, v101, s[10:11]
	v_cmp_lt_i32_e64 s[10:11], -15, v0
	v_cndmask_b32_e32 v88, v88, v158, vcc
	v_cndmask_b32_e64 v89, v89, v158, s[4:5]
	v_cndmask_b32_e64 v102, v158, v102, s[10:11]
	v_cmp_lt_i32_e64 s[10:11], -14, v0
	v_cndmask_b32_e64 v90, v90, v158, s[6:7]
	v_cndmask_b32_e64 v91, v91, v158, s[8:9]
	v_cndmask_b32_e64 v103, v158, v103, s[10:11]
	v_cmp_gt_i32_e64 s[10:11], 16, v0
	v_cmp_gt_i32_e64 s[12:13], 17, v0
	v_cmp_gt_i32_e64 s[14:15], 18, v0
	v_cndmask_b32_e64 v84, v84, v158, s[10:11]
	v_cndmask_b32_e64 v104, v104, v158, s[10:11]
	v_cmp_lt_i32_e64 s[10:11], 47, v0
	v_cmp_gt_i32_e64 s[16:17], 19, v0
	v_cndmask_b32_e32 v80, v80, v158, vcc
	v_cndmask_b32_e64 v92, v158, v92, s[10:11]
	v_cmp_lt_i32_e64 s[10:11], 48, v0
	v_cndmask_b32_e64 v81, v81, v158, s[4:5]
	v_cndmask_b32_e64 v82, v82, v158, s[6:7]
	v_cndmask_b32_e64 v93, v158, v93, s[10:11]
	v_cmp_lt_i32_e64 s[10:11], 49, v0
	v_cndmask_b32_e64 v83, v83, v158, s[8:9]
	v_cmp_gt_i32_e32 vcc, 32, v0
	v_cmp_gt_i32_e64 s[4:5], 33, v0
	v_cmp_gt_i32_e64 s[6:7], 34, v0
	v_cmp_gt_i32_e64 s[8:9], 35, v0
	v_cndmask_b32_e64 v94, v158, v94, s[10:11]
	v_cmp_lt_i32_e64 s[10:11], 50, v0
	v_cndmask_b32_e64 v85, v85, v158, s[12:13]
	v_cndmask_b32_e64 v86, v86, v158, s[14:15]
	v_cndmask_b32_e64 v87, v87, v158, s[16:17]
	v_cndmask_b32_e32 v108, v108, v158, vcc
	v_cndmask_b32_e64 v109, v109, v158, s[4:5]
	v_cndmask_b32_e64 v110, v110, v158, s[6:7]
	v_cndmask_b32_e64 v111, v111, v158, s[8:9]
	v_cndmask_b32_e64 v105, v105, v158, s[12:13]
	v_cndmask_b32_e64 v106, v106, v158, s[14:15]
	v_cndmask_b32_e64 v107, v107, v158, s[16:17]
	v_cndmask_b32_e64 v95, v158, v95, s[10:11]
	v_cndmask_b32_e32 v96, v96, v158, vcc
	v_cndmask_b32_e64 v97, v97, v158, s[4:5]
	v_cndmask_b32_e64 v98, v98, v158, s[6:7]
	v_cndmask_b32_e64 v99, v99, v158, s[8:9]
